# partial drain (vmcnt(16)) of the previous tile's stores before the FFN-up / projection main loops
# baseline (speedup 1.0000x reference)
.LBB0_233:
	s_ashr_i32 s15, s14, 31
	s_lshl_b64 s[16:17], s[14:15], 19
	s_add_u32 s16, s26, s16
	s_addc_u32 s17, s27, s17
	s_and_b64 s[18:19], s[4:5], exec
	s_cselect_b32 s15, s17, s21
	s_cselect_b32 s42, s16, s20
	s_ashr_i32 s13, s12, 31
	s_lshl_b64 s[18:19], s[12:13], 19
	s_add_u32 s18, s28, s18
	s_addc_u32 s19, s29, s19
	s_and_b64 s[24:25], s[4:5], exec
	s_cselect_b32 s13, s19, s23
	s_cselect_b32 s43, s18, s22
	s_add_u32 s20, s20, 0x40080
	s_addc_u32 s21, s21, 0
	s_add_u32 s44, s22, 0x100
	v_mov_b32_e32 v2, 0
	s_addc_u32 s45, s23, 0
	s_mov_b32 s46, -2
	v_mov_b32_e32 v3, v2
	v_mov_b32_e32 v4, v2
	v_mov_b32_e32 v5, v2
	v_mov_b32_e32 v6, v2
	v_mov_b32_e32 v7, v2
	v_mov_b32_e32 v8, v2
	v_mov_b32_e32 v9, v2
	v_mov_b32_e32 v18, v2
	v_mov_b32_e32 v19, v2
	v_mov_b32_e32 v20, v2
	v_mov_b32_e32 v21, v2
	v_mov_b32_e32 v22, v2
	v_mov_b32_e32 v23, v2
	v_mov_b32_e32 v24, v2
	v_mov_b32_e32 v25, v2
	v_mov_b32_e32 v34, v2
	v_mov_b32_e32 v35, v2
	v_mov_b32_e32 v36, v2
	v_mov_b32_e32 v37, v2
	v_mov_b32_e32 v38, v2
	v_mov_b32_e32 v39, v2
	v_mov_b32_e32 v40, v2
	v_mov_b32_e32 v41, v2
	v_mov_b32_e32 v50, v2
	v_mov_b32_e32 v51, v2
	v_mov_b32_e32 v52, v2
	v_mov_b32_e32 v53, v2
	v_mov_b32_e32 v54, v2
	v_mov_b32_e32 v55, v2
	v_mov_b32_e32 v56, v2
	v_mov_b32_e32 v57, v2
	v_mov_b32_e32 v10, v2
	v_mov_b32_e32 v11, v2
	v_mov_b32_e32 v12, v2
	v_mov_b32_e32 v13, v2
	v_mov_b32_e32 v14, v2
	v_mov_b32_e32 v15, v2
	v_mov_b32_e32 v16, v2
	v_mov_b32_e32 v17, v2
	v_mov_b32_e32 v26, v2
	v_mov_b32_e32 v27, v2
	v_mov_b32_e32 v28, v2
	v_mov_b32_e32 v29, v2
	v_mov_b32_e32 v30, v2
	v_mov_b32_e32 v31, v2
	v_mov_b32_e32 v32, v2
	v_mov_b32_e32 v33, v2
	v_mov_b32_e32 v42, v2
	v_mov_b32_e32 v43, v2
	v_mov_b32_e32 v44, v2
	v_mov_b32_e32 v45, v2
	v_mov_b32_e32 v46, v2
	v_mov_b32_e32 v47, v2
	v_mov_b32_e32 v48, v2
	v_mov_b32_e32 v49, v2
	v_mov_b32_e32 v58, v2
	v_mov_b32_e32 v59, v2
	v_mov_b32_e32 v60, v2
	v_mov_b32_e32 v61, v2
	v_mov_b32_e32 v62, v2
	v_mov_b32_e32 v63, v2
	v_mov_b32_e32 v64, v2
	v_mov_b32_e32 v65, v2
	v_mov_b32_e32 v66, v2
	v_mov_b32_e32 v67, v2
	v_mov_b32_e32 v68, v2
	v_mov_b32_e32 v69, v2
	v_mov_b32_e32 v70, v2
	v_mov_b32_e32 v71, v2
	v_mov_b32_e32 v72, v2
	v_mov_b32_e32 v73, v2
	v_mov_b32_e32 v82, v2
	v_mov_b32_e32 v83, v2
	v_mov_b32_e32 v84, v2
	v_mov_b32_e32 v85, v2
	v_mov_b32_e32 v86, v2
	v_mov_b32_e32 v87, v2
	v_mov_b32_e32 v88, v2
	v_mov_b32_e32 v89, v2
	v_mov_b32_e32 v98, v2
	v_mov_b32_e32 v99, v2
	v_mov_b32_e32 v100, v2
	v_mov_b32_e32 v101, v2
	v_mov_b32_e32 v102, v2
	v_mov_b32_e32 v103, v2
	v_mov_b32_e32 v104, v2
	v_mov_b32_e32 v105, v2
	v_mov_b32_e32 v114, v2
	v_mov_b32_e32 v115, v2
	v_mov_b32_e32 v116, v2
	v_mov_b32_e32 v117, v2
	v_mov_b32_e32 v118, v2
	v_mov_b32_e32 v119, v2
	v_mov_b32_e32 v120, v2
	v_mov_b32_e32 v121, v2
	v_mov_b32_e32 v74, v2
	v_mov_b32_e32 v75, v2
	v_mov_b32_e32 v76, v2
	v_mov_b32_e32 v77, v2
	v_mov_b32_e32 v78, v2
	v_mov_b32_e32 v79, v2
	v_mov_b32_e32 v80, v2
	v_mov_b32_e32 v81, v2
	v_mov_b32_e32 v90, v2
	v_mov_b32_e32 v91, v2
	v_mov_b32_e32 v92, v2
	v_mov_b32_e32 v93, v2
	v_mov_b32_e32 v94, v2
	v_mov_b32_e32 v95, v2
	v_mov_b32_e32 v96, v2
	v_mov_b32_e32 v97, v2
	v_mov_b32_e32 v106, v2
	v_mov_b32_e32 v107, v2
	v_mov_b32_e32 v108, v2
	v_mov_b32_e32 v109, v2
	v_mov_b32_e32 v110, v2
	v_mov_b32_e32 v111, v2
	v_mov_b32_e32 v112, v2
	v_mov_b32_e32 v113, v2
	v_mov_b32_e32 v122, v2
	v_mov_b32_e32 v123, v2
	v_mov_b32_e32 v124, v2
	v_mov_b32_e32 v125, v2
	v_mov_b32_e32 v126, v2
	v_mov_b32_e32 v127, v2
	v_mov_b32_e32 v128, v2
	v_mov_b32_e32 v129, v2
	s_waitcnt vmcnt(16)

.LBB0_393:
	s_ashr_i32 s17, s16, 31
	s_lshl_b64 s[18:19], s[16:17], 19
	s_add_u32 s18, s26, s18
	s_addc_u32 s19, s27, s19
	s_and_b64 s[20:21], s[8:9], exec
	s_cselect_b32 s17, s19, s11
	s_cselect_b32 s42, s18, s10
	s_ashr_i32 s15, s14, 31
	s_lshl_b64 s[20:21], s[14:15], 19
	s_add_u32 s20, s28, s20
	s_addc_u32 s21, s29, s21
	s_and_b64 s[24:25], s[8:9], exec
	s_cselect_b32 s15, s21, s23
	s_cselect_b32 s43, s20, s22
	s_add_u32 s10, s10, 0x40080
	s_addc_u32 s11, s11, 0
	s_add_u32 s44, s22, 0x100
	v_mov_b32_e32 v2, 0
	s_addc_u32 s45, s23, 0
	s_mov_b32 s46, -2
	v_mov_b32_e32 v3, v2
	v_mov_b32_e32 v4, v2
	v_mov_b32_e32 v5, v2
	v_mov_b32_e32 v6, v2
	v_mov_b32_e32 v7, v2
	v_mov_b32_e32 v8, v2
	v_mov_b32_e32 v9, v2
	v_mov_b32_e32 v18, v2
	v_mov_b32_e32 v19, v2
	v_mov_b32_e32 v20, v2
	v_mov_b32_e32 v21, v2
	v_mov_b32_e32 v22, v2
	v_mov_b32_e32 v23, v2
	v_mov_b32_e32 v24, v2
	v_mov_b32_e32 v25, v2
	v_mov_b32_e32 v34, v2
	v_mov_b32_e32 v35, v2
	v_mov_b32_e32 v36, v2
	v_mov_b32_e32 v37, v2
	v_mov_b32_e32 v38, v2
	v_mov_b32_e32 v39, v2
	v_mov_b32_e32 v40, v2
	v_mov_b32_e32 v41, v2
	v_mov_b32_e32 v50, v2
	v_mov_b32_e32 v51, v2
	v_mov_b32_e32 v52, v2
	v_mov_b32_e32 v53, v2
	v_mov_b32_e32 v54, v2
	v_mov_b32_e32 v55, v2
	v_mov_b32_e32 v56, v2
	v_mov_b32_e32 v57, v2
	v_mov_b32_e32 v10, v2
	v_mov_b32_e32 v11, v2
	v_mov_b32_e32 v12, v2
	v_mov_b32_e32 v13, v2
	v_mov_b32_e32 v14, v2
	v_mov_b32_e32 v15, v2
	v_mov_b32_e32 v16, v2
	v_mov_b32_e32 v17, v2
	v_mov_b32_e32 v26, v2
	v_mov_b32_e32 v27, v2
	v_mov_b32_e32 v28, v2
	v_mov_b32_e32 v29, v2
	v_mov_b32_e32 v30, v2
	v_mov_b32_e32 v31, v2
	v_mov_b32_e32 v32, v2
	v_mov_b32_e32 v33, v2
	v_mov_b32_e32 v42, v2
	v_mov_b32_e32 v43, v2
	v_mov_b32_e32 v44, v2
	v_mov_b32_e32 v45, v2
	v_mov_b32_e32 v46, v2
	v_mov_b32_e32 v47, v2
	v_mov_b32_e32 v48, v2
	v_mov_b32_e32 v49, v2
	v_mov_b32_e32 v58, v2
	v_mov_b32_e32 v59, v2
	v_mov_b32_e32 v60, v2
	v_mov_b32_e32 v61, v2
	v_mov_b32_e32 v62, v2
	v_mov_b32_e32 v63, v2
	v_mov_b32_e32 v64, v2
	v_mov_b32_e32 v65, v2
	v_mov_b32_e32 v66, v2
	v_mov_b32_e32 v67, v2
	v_mov_b32_e32 v68, v2
	v_mov_b32_e32 v69, v2
	v_mov_b32_e32 v70, v2
	v_mov_b32_e32 v71, v2
	v_mov_b32_e32 v72, v2
	v_mov_b32_e32 v73, v2
	v_mov_b32_e32 v82, v2
	v_mov_b32_e32 v83, v2
	v_mov_b32_e32 v84, v2
	v_mov_b32_e32 v85, v2
	v_mov_b32_e32 v86, v2
	v_mov_b32_e32 v87, v2
	v_mov_b32_e32 v88, v2
	v_mov_b32_e32 v89, v2
	v_mov_b32_e32 v98, v2
	v_mov_b32_e32 v99, v2
	v_mov_b32_e32 v100, v2
	v_mov_b32_e32 v101, v2
	v_mov_b32_e32 v102, v2
	v_mov_b32_e32 v103, v2
	v_mov_b32_e32 v104, v2
	v_mov_b32_e32 v105, v2
	v_mov_b32_e32 v114, v2
	v_mov_b32_e32 v115, v2
	v_mov_b32_e32 v116, v2
	v_mov_b32_e32 v117, v2
	v_mov_b32_e32 v118, v2
	v_mov_b32_e32 v119, v2
	v_mov_b32_e32 v120, v2
	v_mov_b32_e32 v121, v2
	v_mov_b32_e32 v74, v2
	v_mov_b32_e32 v75, v2
	v_mov_b32_e32 v76, v2
	v_mov_b32_e32 v77, v2
	v_mov_b32_e32 v78, v2
	v_mov_b32_e32 v79, v2
	v_mov_b32_e32 v80, v2
	v_mov_b32_e32 v81, v2
	v_mov_b32_e32 v90, v2
	v_mov_b32_e32 v91, v2
	v_mov_b32_e32 v92, v2
	v_mov_b32_e32 v93, v2
	v_mov_b32_e32 v94, v2
	v_mov_b32_e32 v95, v2
	v_mov_b32_e32 v96, v2
	v_mov_b32_e32 v97, v2
	v_mov_b32_e32 v106, v2
	v_mov_b32_e32 v107, v2
	v_mov_b32_e32 v108, v2
	v_mov_b32_e32 v109, v2
	v_mov_b32_e32 v110, v2
	v_mov_b32_e32 v111, v2
	v_mov_b32_e32 v112, v2
	v_mov_b32_e32 v113, v2
	v_mov_b32_e32 v122, v2
	v_mov_b32_e32 v123, v2
	v_mov_b32_e32 v124, v2
	v_mov_b32_e32 v125, v2
	v_mov_b32_e32 v126, v2
	v_mov_b32_e32 v127, v2
	v_mov_b32_e32 v128, v2
	v_mov_b32_e32 v129, v2
	s_waitcnt vmcnt(16)

.LBB0_1601:
	s_ashr_i32 s15, s14, 31
	s_lshl_b64 s[16:17], s[14:15], 19
	s_add_u32 s16, s26, s16
	s_addc_u32 s17, s27, s17
	s_and_b64 s[18:19], s[6:7], exec
	s_cselect_b32 s15, s17, s21
	s_cselect_b32 s42, s16, s20
	s_ashr_i32 s13, s12, 31
	s_lshl_b64 s[18:19], s[12:13], 19
	s_add_u32 s18, s28, s18
	s_addc_u32 s19, s29, s19
	s_and_b64 s[24:25], s[6:7], exec
	s_cselect_b32 s13, s19, s23
	s_cselect_b32 s43, s18, s22
	s_add_u32 s20, s20, 0x40080
	s_addc_u32 s21, s21, 0
	s_add_u32 s44, s22, 0x100
	v_mov_b32_e32 v2, 0
	s_addc_u32 s45, s23, 0
	s_mov_b32 s46, -2
	v_mov_b32_e32 v3, v2
	v_mov_b32_e32 v4, v2
	v_mov_b32_e32 v5, v2
	v_mov_b32_e32 v6, v2
	v_mov_b32_e32 v7, v2
	v_mov_b32_e32 v8, v2
	v_mov_b32_e32 v9, v2
	v_mov_b32_e32 v18, v2
	v_mov_b32_e32 v19, v2
	v_mov_b32_e32 v20, v2
	v_mov_b32_e32 v21, v2
	v_mov_b32_e32 v22, v2
	v_mov_b32_e32 v23, v2
	v_mov_b32_e32 v24, v2
	v_mov_b32_e32 v25, v2
	v_mov_b32_e32 v34, v2
	v_mov_b32_e32 v35, v2
	v_mov_b32_e32 v36, v2
	v_mov_b32_e32 v37, v2
	v_mov_b32_e32 v38, v2
	v_mov_b32_e32 v39, v2
	v_mov_b32_e32 v40, v2
	v_mov_b32_e32 v41, v2
	v_mov_b32_e32 v50, v2
	v_mov_b32_e32 v51, v2
	v_mov_b32_e32 v52, v2
	v_mov_b32_e32 v53, v2
	v_mov_b32_e32 v54, v2
	v_mov_b32_e32 v55, v2
	v_mov_b32_e32 v56, v2
	v_mov_b32_e32 v57, v2
	v_mov_b32_e32 v10, v2
	v_mov_b32_e32 v11, v2
	v_mov_b32_e32 v12, v2
	v_mov_b32_e32 v13, v2
	v_mov_b32_e32 v14, v2
	v_mov_b32_e32 v15, v2
	v_mov_b32_e32 v16, v2
	v_mov_b32_e32 v17, v2
	v_mov_b32_e32 v26, v2
	v_mov_b32_e32 v27, v2
	v_mov_b32_e32 v28, v2
	v_mov_b32_e32 v29, v2
	v_mov_b32_e32 v30, v2
	v_mov_b32_e32 v31, v2
	v_mov_b32_e32 v32, v2
	v_mov_b32_e32 v33, v2
	v_mov_b32_e32 v42, v2
	v_mov_b32_e32 v43, v2
	v_mov_b32_e32 v44, v2
	v_mov_b32_e32 v45, v2
	v_mov_b32_e32 v46, v2
	v_mov_b32_e32 v47, v2
	v_mov_b32_e32 v48, v2
	v_mov_b32_e32 v49, v2
	v_mov_b32_e32 v58, v2
	v_mov_b32_e32 v59, v2
	v_mov_b32_e32 v60, v2
	v_mov_b32_e32 v61, v2
	v_mov_b32_e32 v62, v2
	v_mov_b32_e32 v63, v2
	v_mov_b32_e32 v64, v2
	v_mov_b32_e32 v65, v2
	v_mov_b32_e32 v66, v2
	v_mov_b32_e32 v67, v2
	v_mov_b32_e32 v68, v2
	v_mov_b32_e32 v69, v2
	v_mov_b32_e32 v70, v2
	v_mov_b32_e32 v71, v2
	v_mov_b32_e32 v72, v2
	v_mov_b32_e32 v73, v2
	v_mov_b32_e32 v82, v2
	v_mov_b32_e32 v83, v2
	v_mov_b32_e32 v84, v2
	v_mov_b32_e32 v85, v2
	v_mov_b32_e32 v86, v2
	v_mov_b32_e32 v87, v2
	v_mov_b32_e32 v88, v2
	v_mov_b32_e32 v89, v2
	v_mov_b32_e32 v98, v2
	v_mov_b32_e32 v99, v2
	v_mov_b32_e32 v100, v2
	v_mov_b32_e32 v101, v2
	v_mov_b32_e32 v102, v2
	v_mov_b32_e32 v103, v2
	v_mov_b32_e32 v104, v2
	v_mov_b32_e32 v105, v2
	v_mov_b32_e32 v114, v2
	v_mov_b32_e32 v115, v2
	v_mov_b32_e32 v116, v2
	v_mov_b32_e32 v117, v2
	v_mov_b32_e32 v118, v2
	v_mov_b32_e32 v119, v2
	v_mov_b32_e32 v120, v2
	v_mov_b32_e32 v121, v2
	v_mov_b32_e32 v74, v2
	v_mov_b32_e32 v75, v2
	v_mov_b32_e32 v76, v2
	v_mov_b32_e32 v77, v2
	v_mov_b32_e32 v78, v2
	v_mov_b32_e32 v79, v2
	v_mov_b32_e32 v80, v2
	v_mov_b32_e32 v81, v2
	v_mov_b32_e32 v90, v2
	v_mov_b32_e32 v91, v2
	v_mov_b32_e32 v92, v2
	v_mov_b32_e32 v93, v2
	v_mov_b32_e32 v94, v2
	v_mov_b32_e32 v95, v2
	v_mov_b32_e32 v96, v2
	v_mov_b32_e32 v97, v2
	v_mov_b32_e32 v106, v2
	v_mov_b32_e32 v107, v2
	v_mov_b32_e32 v108, v2
	v_mov_b32_e32 v109, v2
	v_mov_b32_e32 v110, v2
	v_mov_b32_e32 v111, v2
	v_mov_b32_e32 v112, v2
	v_mov_b32_e32 v113, v2
	v_mov_b32_e32 v122, v2
	v_mov_b32_e32 v123, v2
	v_mov_b32_e32 v124, v2
	v_mov_b32_e32 v125, v2
	v_mov_b32_e32 v126, v2
	v_mov_b32_e32 v127, v2
	v_mov_b32_e32 v128, v2
	v_mov_b32_e32 v129, v2
	s_waitcnt vmcnt(16)
